# MLA attention: issue K-fragment LDS reads before the next-tile global loads at the top of each KV tile
# speedup vs baseline: 1.0447x; 1.0002x over previous
; #define PIN() do { asm volatile("" ::: "memory"); __builtin_amdgcn_sched_barrier(0); } while (0)
; #define GLOAD(kt_) do { const bf16_t* kp_ = Kb + (size_t)(kt_) * 64 * DQK; const bf16_t* vp_ = VTb + (kt_) * 64; \
;     kreg0 = *(const uint4*)(kp_ + kgo[0]); kreg1 = *(const uint4*)(kp_ + kgo[1]); if (NKC > 2) kreg2 = *(const uint4*)(kp_ + kgo[2]); \
;     vreg0 = *(const uint4*)(vp_ + vgo0); vreg1 = *(const uint4*)(vp_ + vgo1); } while (0)
; #define KLD(dst_, s_) do { dst_[0] = *(const bf16x8*)(kbase + (s_) * 32); dst_[1] = *(const bf16x8*)(kbase + 32 * KSTR + (s_) * 32); \
;         dst_[2] = *(const bf16x8*)(kbase + ((s_) + 1) * 32); dst_[3] = *(const bf16x8*)(kbase + 32 * KSTR + ((s_) + 1) * 32); } while (0)
; template <int DQK, int NM>
; DI void attn_item(const bf16_t* Qb, const bf16_t* Kb, size_t mstride, const bf16_t* VTb,
;                   int q0, int nkt, float cs, bf16_t* Orow  , float lam, float outscale, const float* subw, char* smem) {
;     ...
;   for (int kt = 0; kt < nkt; ++kt) {
;     const char* cur = smem + (kt & 1) * BUF;
;     GLOAD(kt + 1 < nkt ? kt + 1 : kt);
;     PIN();
;     f32x16 sacc[2];
; #pragma unroll
;     for (int kb = 0; kb < 2; ++kb)
; #pragma unroll
;       for (int i = 0; i < 16; ++i) sacc[kb][i] = 0.f;
;     const char* kbase = cur + (m * 64 + l31) * KSTR + hh * 16;
;     {
;       bf16x8 kfa[4], kfb[4];
;     ...
;       KLD(kfa, 0);
; #pragma unroll
;       for (int g = 0; g < NS / 2; ++g) {
;         PIN();
;         if (g + 1 < NS / 2) { if (g & 1) KLD(kfa, 2 * g + 2); else KLD(kfb, 2 * g + 2); }
;         PIN();
;         if (g & 1) KMM(kfb, 2 * g); else KMM(kfa, 2 * g);
;       }
;     ...
;     }
;     float mx = sacc[0][0];
; #pragma unroll
;     for (int i = 1; i < 16; ++i) mx = fmaxf(mx, sacc[0][i]);
; #pragma unroll
;     for (int i = 0; i < 16; ++i) mx = fmaxf(mx, sacc[1][i]);
;     {
;       const auto rr = __builtin_amdgcn_permlane32_swap(__float_as_uint(mx), __float_as_uint(mx), false, false);
;       mx = fmaxf(__uint_as_float(rr[0]), __uint_as_float(rr[1]));
;     }
;     if (__any((mx - mrun) * cs > 8.f)) {
;       const float mnew = fmaxf(mrun, mx);
;       const float alpha = __builtin_amdgcn_exp2f((mrun - mnew) * cs);
;       mrun = mnew;
;       lrun *= alpha;
; #pragma unroll
;       for (int db = 0; db < 4; ++db)
; #pragma unroll
;         for (int i = 0; i < 16; ++i) oacc[db][i] *= alpha;
;     }
.LBB0_127:
	s_and_b32 s24, 1, s37
	s_cselect_b32 s25, 0, 0xac00
	s_add_i32 s25, s25, 0
	v_add3_u32 v196, s25, v217, v170
	ds_read_b128 v[64:67], v196
	ds_read_b128 v[220:223], v196 offset:32
	ds_read_b128 v[68:71], v196 offset:12800
	ds_read_b128 v[224:227], v196 offset:12832
	ds_read_b128 v[228:231], v196 offset:64
	ds_read_b128 v[232:235], v196 offset:96
	ds_read_b128 v[236:239], v196 offset:12864
	ds_read_b128 v[240:243], v196 offset:12896
	v_lshl_add_u64 v[80:81], s[20:21], 0, v[190:191]
	v_lshl_add_u64 v[82:83], s[20:21], 0, v[192:193]
	global_load_dwordx4 v[158:161], v[80:81], off
	global_load_dwordx4 v[154:157], v[82:83], off
	v_lshl_add_u64 v[80:81], s[20:21], 0, v[194:195]
	s_mov_b32 s32, 0xca06000
	v_add_co_u32_e32 v80, vcc, s32, v80
	v_lshl_add_u64 v[82:83], s[20:21], 0, v[186:187]
	s_nop 0
	v_addc_co_u32_e32 v81, vcc, 0, v81, vcc
	global_load_dwordx4 v[162:165], v[80:81], off
	global_load_dwordx4 v[150:153], v[82:83], off
	v_lshl_add_u64 v[80:81], s[20:21], 0, v[188:189]
	global_load_dwordx4 v[146:149], v[80:81], off
	s_waitcnt lgkmcnt(7)
	v_mfma_f32_32x32x16_bf16 v[80:95], v[64:67], v[142:145], 0
	s_waitcnt lgkmcnt(5)
	v_mfma_f32_32x32x16_bf16 v[64:79], v[68:71], v[142:145], 0
	v_mfma_f32_32x32x16_bf16 v[80:95], v[220:223], v[136:139], v[80:95]
	s_waitcnt lgkmcnt(4)
	v_mfma_f32_32x32x16_bf16 v[64:79], v[224:227], v[136:139], v[64:79]
	ds_read_b128 v[220:223], v196 offset:128
	ds_read_b128 v[224:227], v196 offset:160
	ds_read_b128 v[244:247], v196 offset:12928
	ds_read_b128 v[248:251], v196 offset:12960
	s_waitcnt lgkmcnt(7)
	v_mfma_f32_32x32x16_bf16 v[80:95], v[228:231], v[132:135], v[80:95]
	s_waitcnt lgkmcnt(5)
	v_mfma_f32_32x32x16_bf16 v[64:79], v[236:239], v[132:135], v[64:79]
	v_mfma_f32_32x32x16_bf16 v[80:95], v[232:235], v[128:131], v[80:95]
	s_waitcnt lgkmcnt(4)
	v_mfma_f32_32x32x16_bf16 v[64:79], v[240:243], v[128:131], v[64:79]
	ds_read_b128 v[228:231], v196 offset:192
	ds_read_b128 v[232:235], v196 offset:224
	ds_read_b128 v[236:239], v196 offset:12992
	ds_read_b128 v[240:243], v196 offset:13024
	s_waitcnt lgkmcnt(7)
	v_mfma_f32_32x32x16_bf16 v[80:95], v[220:223], v[124:127], v[80:95]
	s_waitcnt lgkmcnt(5)
	v_mfma_f32_32x32x16_bf16 v[64:79], v[244:247], v[124:127], v[64:79]
	v_mfma_f32_32x32x16_bf16 v[80:95], v[224:227], v[120:123], v[80:95]
	s_waitcnt lgkmcnt(4)
	v_mfma_f32_32x32x16_bf16 v[64:79], v[248:251], v[120:123], v[64:79]
	ds_read_b128 v[220:223], v196 offset:256
	ds_read_b128 v[224:227], v196 offset:288
	ds_read_b128 v[244:247], v196 offset:13056
	ds_read_b128 v[248:251], v196 offset:13088
	s_waitcnt lgkmcnt(7)
	v_mfma_f32_32x32x16_bf16 v[80:95], v[228:231], v[116:119], v[80:95]
	s_waitcnt lgkmcnt(5)
	v_mfma_f32_32x32x16_bf16 v[64:79], v[236:239], v[116:119], v[64:79]
	v_mfma_f32_32x32x16_bf16 v[80:95], v[232:235], v[112:115], v[80:95]
	s_waitcnt lgkmcnt(4)
	v_mfma_f32_32x32x16_bf16 v[64:79], v[240:243], v[112:115], v[64:79]
	ds_read_b128 v[228:231], v196 offset:320
	ds_read_b128 v[232:235], v196 offset:352
	ds_read_b128 v[236:239], v196 offset:13120
	ds_read_b128 v[240:243], v196 offset:13152
	s_waitcnt lgkmcnt(7)
	v_mfma_f32_32x32x16_bf16 v[80:95], v[220:223], v[108:111], v[80:95]
	s_waitcnt lgkmcnt(5)
	v_mfma_f32_32x32x16_bf16 v[64:79], v[244:247], v[108:111], v[64:79]
	v_mfma_f32_32x32x16_bf16 v[80:95], v[224:227], v[104:107], v[80:95]
	s_waitcnt lgkmcnt(4)
	v_mfma_f32_32x32x16_bf16 v[64:79], v[248:251], v[104:107], v[64:79]
	s_waitcnt lgkmcnt(3)
	v_mfma_f32_32x32x16_bf16 v[80:95], v[228:231], v[100:103], v[80:95]
	s_waitcnt lgkmcnt(2)
	v_mfma_f32_32x32x16_bf16 v[80:95], v[232:235], v[96:99], v[80:95]
	s_waitcnt lgkmcnt(1)
	v_mfma_f32_32x32x16_bf16 v[64:79], v[236:239], v[100:103], v[64:79]
	s_nop 9
	v_max_f32_e32 v196, v81, v81
	v_max_f32_e32 v219, v80, v80
	v_max_f32_e32 v196, v219, v196
	v_max3_f32 v196, v196, v82, v83
	v_max3_f32 v196, v196, v84, v85
	v_max3_f32 v196, v196, v86, v87
	v_max3_f32 v196, v196, v88, v89
	s_waitcnt lgkmcnt(0)
	v_mfma_f32_32x32x16_bf16 v[64:79], v[240:243], v[96:99], v[64:79]
	v_max3_f32 v196, v196, v90, v91
	v_max3_f32 v196, v196, v92, v93
	v_max3_f32 v196, v196, v94, v95
	s_nop 8
	v_max3_f32 v196, v196, v64, v65
	v_max3_f32 v196, v196, v66, v67
	v_max3_f32 v196, v196, v68, v69
	v_max3_f32 v196, v196, v70, v71
	v_max3_f32 v196, v196, v72, v73
	v_max3_f32 v196, v196, v74, v75
	v_max3_f32 v196, v196, v76, v77
	v_max3_f32 v196, v196, v78, v79
	v_mov_b32_e32 v219, v196
	s_nop 1
	v_permlane32_swap_b32_e32 v196, v219
	v_max_f32_e32 v219, v219, v219
	v_max_f32_e32 v196, v196, v196
	v_max_f32_e32 v196, v196, v219
	v_sub_f32_e32 v219, v196, v218
	v_mul_f32_e32 v219, 0x3dd53b95, v219
	v_cmp_lt_f32_e32 vcc, s5, v219
	s_cbranch_vccz .LBB0_126
	v_max_f32_e32 v196, v196, v196
	v_max_f32_e32 v219, v218, v218
	v_max_f32_e32 v219, v219, v196
	v_sub_f32_e32 v196, v218, v219
	v_mul_f32_e32 v196, 0x3dd53b95, v196
	v_exp_f32_e32 v196, v196
	v_mov_b32_e32 v218, v219
	v_pk_mul_f32 v[46:47], v[46:47], v[196:197] op_sel_hi:[1,0]
	v_pk_mul_f32 v[44:45], v[44:45], v[196:197] op_sel_hi:[1,0]
	v_pk_mul_f32 v[42:43], v[42:43], v[196:197] op_sel_hi:[1,0]
	v_pk_mul_f32 v[40:41], v[40:41], v[196:197] op_sel_hi:[1,0]
	v_pk_mul_f32 v[38:39], v[38:39], v[196:197] op_sel_hi:[1,0]
	v_pk_mul_f32 v[36:37], v[36:37], v[196:197] op_sel_hi:[1,0]
	v_pk_mul_f32 v[34:35], v[34:35], v[196:197] op_sel_hi:[1,0]
	v_pk_mul_f32 v[32:33], v[32:33], v[196:197] op_sel_hi:[1,0]
	v_pk_mul_f32 v[62:63], v[62:63], v[196:197] op_sel_hi:[1,0]
	v_pk_mul_f32 v[60:61], v[60:61], v[196:197] op_sel_hi:[1,0]
	v_pk_mul_f32 v[58:59], v[58:59], v[196:197] op_sel_hi:[1,0]
	v_pk_mul_f32 v[56:57], v[56:57], v[196:197] op_sel_hi:[1,0]
	v_pk_mul_f32 v[54:55], v[54:55], v[196:197] op_sel_hi:[1,0]
	v_pk_mul_f32 v[52:53], v[52:53], v[196:197] op_sel_hi:[1,0]
	v_pk_mul_f32 v[50:51], v[50:51], v[196:197] op_sel_hi:[1,0]
	v_pk_mul_f32 v[48:49], v[48:49], v[196:197] op_sel_hi:[1,0]
	v_pk_mul_f32 v[30:31], v[30:31], v[196:197] op_sel_hi:[1,0]
	v_pk_mul_f32 v[28:29], v[28:29], v[196:197] op_sel_hi:[1,0]
	v_pk_mul_f32 v[26:27], v[26:27], v[196:197] op_sel_hi:[1,0]
	v_pk_mul_f32 v[24:25], v[24:25], v[196:197] op_sel_hi:[1,0]
	v_pk_mul_f32 v[22:23], v[22:23], v[196:197] op_sel_hi:[1,0]
	v_pk_mul_f32 v[20:21], v[20:21], v[196:197] op_sel_hi:[1,0]
	v_pk_mul_f32 v[18:19], v[18:19], v[196:197] op_sel_hi:[1,0]
	v_pk_mul_f32 v[16:17], v[16:17], v[196:197] op_sel_hi:[1,0]
	v_pk_mul_f32 v[14:15], v[14:15], v[196:197] op_sel_hi:[1,0]
	v_pk_mul_f32 v[12:13], v[12:13], v[196:197] op_sel_hi:[1,0]
	v_pk_mul_f32 v[10:11], v[10:11], v[196:197] op_sel_hi:[1,0]
	v_pk_mul_f32 v[8:9], v[8:9], v[196:197] op_sel_hi:[1,0]
	v_pk_mul_f32 v[6:7], v[6:7], v[196:197] op_sel_hi:[1,0]
	v_pk_mul_f32 v[4:5], v[4:5], v[196:197] op_sel_hi:[1,0]
	v_pk_mul_f32 v[2:3], v[2:3], v[196:197] op_sel_hi:[1,0]
	v_pk_mul_f32 v[0:1], v[0:1], v[196:197] op_sel_hi:[1,0]
	v_mul_f32_e32 v185, v185, v196
	s_branch .LBB0_126
